# phase C reorder: retention CUs pull 5 conversion batches before their mixer item (overlap HBM-bound conversion with attention)
# baseline (speedup 1.0000x reference)
; #define PHASE_PROLOG() CArgs* ka = kargs(); unsigned char* ws = ka->ws; (void)ws; const int tid = opaque_tid(), lane = tid & 63, wave = __builtin_amdgcn_readfirstlane(tid >> 6), gw = vcu * NWAVES + wave; (void)lane; (void)gw
; __global__ void __launch_bounds__(NWAVES * 64, 2) fwd_kernel(Args args_unused) {
;     ...
;         for (int rep = 0; rep < ((DUPMASK & 8) ? 2 : 1); ++rep)
;         for (int item = bx; item < 128 + 128; item += G) {
;             PHASE_PROLOG();
;             const bf16* Z = (const bf16*)(ws + WS_Z); bf16* MIX = (bf16*)(ws + WS_MIX);
;             if (item < 128) retention_item(lds, Z, (bf16*)(ws + WS_YF), MIX, ka->in[6] + (size_t)layer * 2 * NH, ka->in[7] + (size_t)layer * 2048, (unsigned long long*)(ws + WS_EXP), (unsigned*)(ws + WS_CTL) + CW_FLAG + 4096 * layer, item, tid);
;             else attention_item(lds, Z, (bf16*)(ws + WS_OP), (float*)(ws + WS_LP), MIX, ka->in[8] + (size_t)layer * HD, ka->in[9] + (size_t)layer * HD, item - 128, tid);
;         }
.LBB0_327:
	s_or_b64 exec, exec, s[6:7]
	v_readlane_b32 s6, v254, 11
	v_readlane_b32 s7, v254, 12
	s_andn2_b64 vcc, exec, s[6:7]
	s_waitcnt lgkmcnt(0)
	s_barrier
	s_cbranch_vccnz .LBB0_1282
	s_cmpk_gt_i32 s2, 0x7f
	s_cbranch_scc1 .Lc_mix_entry
	v_lshlrev_b32_e32 v2, 2, v0
	v_add_u32_e32 v2, 0x23580, v2
	ds_read_b32 v5, v2
	s_waitcnt lgkmcnt(0)
	v_readfirstlane_b32 s28, v5
	s_nop 3
	s_cmp_lg_u32 s28, 0
	s_cbranch_scc1 .Lc_mix_entry
	v_mov_b32_e32 v5, 5
	ds_write_b32 v2, v5
	s_waitcnt lgkmcnt(0)
	s_branch .LBB0_1282
.Lc_mix_entry:
	v_readlane_b32 s6, v254, 63
	v_readlane_b32 s7, v255, 0
	s_lshl_b64 s[14:15], s[6:7], 7
	v_readlane_b32 s48, v254, 63
	s_mul_i32 s48, s48, 0x2b00000
	s_mov_b32 s49, s29
	s_lshl_b64 s[10:11], s[6:7], 13
	s_lshl_b32 s28, s6, 12
	v_readlane_b32 s6, v254, 54
	s_lshl_b32 s39, s6, 7
	s_lshl_b64 s[12:13], s[28:29], 2
	s_mov_b32 s43, s2
	v_readlane_b32 s52, v254, 38
	s_mov_b32 s53, s2
	s_branch .LBB0_331

; #define LAS __attribute__((address_space(3)))
; #define PHASE_PROLOG() CArgs* ka = kargs(); unsigned char* ws = ka->ws; (void)ws; const int tid = opaque_tid(), lane = tid & 63, wave = __builtin_amdgcn_readfirstlane(tid >> 6), gw = vcu * NWAVES + wave; (void)lane; (void)gw
; __global__ void __launch_bounds__(NWAVES * 64, 2) fwd_kernel(Args args_unused) {
;     ...
;         {
;             PHASE_PROLOG();
;             LAS float* scr = (LAS float*)(lds + wave * TR_SCR);
;             unsigned* qhead = (unsigned*)(ws + WS_CTL) + CW_QUEUE + 64 * layer;
;             CV_PTRS(P, ka, ws, layer);
;             volatile LAS unsigned* qb = (volatile LAS unsigned*)(lds + MISC_OFF) + 2;
;             for (;;) {
;                 __syncthreads();
;                 if (tid == 0) *qb = atomicAdd(qhead, 32u);
;                 __syncthreads();
;                 const int it0 = CV_A + (int)__builtin_amdgcn_readfirstlane(*qb);
;                 if (it0 >= CV_ALL) break;
;                 for (int k = 0; k < 4; ++k) { const int it = it0 + 8 * k + wave; if (it < CV_ALL) convert_item(P, it, scr, lane); }
.LBB0_1282:
	v_readlane_b32 s48, v254, 63
	s_mul_i32 s48, s48, 0x2b00000
	s_mov_b32 s49, s29
	v_readlane_b32 s6, v254, 0
	v_readlane_b32 s7, v254, 1
	v_mov_b32_e32 v6, v0
	s_load_dwordx2 s[52:53], s[6:7], 0x98
	s_load_dwordx4 s[24:27], s[6:7], 0x20
	v_readfirstlane_b32 s8, v6
	s_ashr_i32 s39, s8, 6
	s_mul_i32 s8, s39, 0x4200
	s_add_i32 s50, s8, 0
	v_readlane_b32 s8, v254, 63
	v_readlane_b32 s9, v255, 0
	s_lshl_b32 s28, s8, 6
	s_lshl_b64 s[8:9], s[28:29], 2
	s_waitcnt lgkmcnt(0)
	s_add_u32 s8, s52, s8
	s_addc_u32 s9, s53, s9
	s_add_u32 s36, s8, 0x2000
	s_addc_u32 s37, s9, 0
	s_load_dwordx16 s[8:23], s[6:7], 0x50
	v_readlane_b32 s6, v254, 59
	v_readlane_b32 s7, v254, 60
	s_lshl_b64 s[6:7], s[6:7], 2
	s_add_u32 s26, s26, s6
	s_addc_u32 s27, s27, s7
	v_readlane_b32 s6, v254, 61
	v_readlane_b32 s7, v254, 62
	s_lshl_b64 s[6:7], s[6:7], 2
	s_waitcnt lgkmcnt(0)
	s_add_u32 s22, s22, s6
	s_addc_u32 s23, s23, s7
	v_readlane_b32 s6, v255, 5
	v_readlane_b32 s7, v255, 6
	s_lshl_b64 s[6:7], s[6:7], 2
	s_add_u32 s40, s8, s6
	s_addc_u32 s41, s9, s7
	s_lshl_b64 s[8:9], s[48:49], 2
	s_add_u32 s12, s12, s8
	s_addc_u32 s13, s13, s9
	s_add_u32 s14, s14, s8
	s_addc_u32 s15, s15, s9
	s_add_u32 s16, s16, s8
	s_addc_u32 s17, s17, s9
	s_add_u32 s20, s20, s6
	s_addc_u32 s21, s21, s7
	v_readlane_b32 s6, v254, 57
	v_readlane_b32 s7, v254, 58
	s_lshl_b64 s[6:7], s[6:7], 2
	s_add_u32 s8, s24, s6
	s_addc_u32 s9, s25, s7
	s_add_u32 s34, s10, s6
	s_addc_u32 s35, s11, s7
	v_readlane_b32 s10, v255, 3
	s_add_u32 s42, s18, s6
	v_readlane_b32 s11, v255, 4
	s_addc_u32 s43, s19, s7
	s_lshl_b64 s[10:11], s[10:11], 2
	s_add_u32 s46, s52, s10
	s_addc_u32 s47, s53, s11
	s_add_u32 s10, s52, 0x6c510000
	s_addc_u32 s11, s53, 0
	s_add_u32 s48, s52, s6
	s_addc_u32 s49, s53, s7
	v_readlane_b32 s6, v255, 1
	s_add_u32 s18, s52, 0x6c525800
	v_readlane_b32 s7, v255, 2
	s_addc_u32 s19, s53, 0
	s_lshl_b64 s[6:7], s[6:7], 2
	s_add_u32 s54, s52, s6
	s_waitcnt vmcnt(16)
	v_and_b32_e32 v122, 7, v6
	v_bfe_u32 v80, v6, 3, 3
	s_addc_u32 s55, s53, s7
	v_cmp_eq_u32_e64 s[6:7], 0, v6
	s_waitcnt vmcnt(1)
	v_bfe_u32 v77, v6, 4, 2
	v_lshlrev_b32_e32 v2, 2, v6
	v_lshlrev_b32_e32 v4, 5, v122
	v_mov_b32_e32 v5, v3
	v_lshlrev_b32_e32 v6, 2, v80
	v_mov_b32_e32 v7, v3
	v_and_b32_e32 v76, 60, v2
	v_lshl_add_u64 v[78:79], s[42:43], 0, v[4:5]
	v_lshl_add_u64 v[8:9], s[48:49], 0, v[6:7]
	s_mov_b64 s[42:43], 0xc0000
	v_lshlrev_b32_e32 v2, 3, v122
	v_lshl_add_u64 v[82:83], v[8:9], 0, s[42:43]
	v_mul_u32_u24_e32 v8, 0x104, v77
	v_lshlrev_b32_e32 v9, 2, v76
	v_lshl_add_u64 v[102:103], s[34:35], 0, v[4:5]
	v_lshl_add_u64 v[12:13], s[46:47], 0, v[6:7]
	s_mov_b64 s[34:35], 0x4ac00
	s_add_u32 s44, s52, 0x6c529800
	v_add3_u32 v123, s50, v8, v9
	v_lshl_add_u64 v[8:9], s[52:53], 0, v[2:3]
	v_lshl_add_u64 v[104:105], v[12:13], 0, s[34:35]
	s_mov_b64 s[34:35], 0x9200000
	s_addc_u32 s45, s53, 0
	v_mul_u32_u24_e32 v10, 0x820, v122
	v_lshlrev_b32_e32 v2, 4, v122
	v_lshl_add_u64 v[106:107], v[8:9], 0, s[34:35]
	s_mov_b64 s[34:35], 0x40000
	v_lshl_add_u64 v[114:115], s[8:9], 0, v[4:5]
	v_lshl_add_u64 v[4:5], s[54:55], 0, v[6:7]
	s_mov_b64 s[8:9], 0x80000
	s_mov_b64 s[42:43], 0x19400000
	v_add3_u32 v124, s50, v10, v6
	v_lshl_add_u64 v[10:11], s[52:53], 0, v[2:3]
	v_lshl_add_u64 v[108:109], v[12:13], 0, s[34:35]
	s_mov_b64 s[34:35], 0x7200000
	s_cmp_eq_u64 s[24:25], 0
	v_lshl_add_u64 v[116:117], v[4:5], 0, s[8:9]
	s_mov_b64 s[8:9], 0x6c52f800
	v_lshl_add_u64 v[84:85], v[8:9], 0, s[42:43]
	s_mov_b64 s[42:43], 0x13e00000
	v_lshl_add_u64 v[110:111], v[10:11], 0, s[34:35]
	s_mov_b64 s[34:35], 0x1b400000
	s_cselect_b64 s[50:51], -1, 0
	s_cmp_lg_u64 s[24:25], 0
	v_lshl_add_u64 v[118:119], v[8:9], 0, s[8:9]
	s_mov_b64 s[8:9], 0x200000
	v_mov_b32_e32 v81, v3
	v_or_b32_e32 v86, 8, v80
	v_or_b32_e32 v88, 16, v80
	v_or_b32_e32 v90, 24, v80
	v_or_b32_e32 v92, 32, v80
	v_or_b32_e32 v94, 40, v80
	v_or_b32_e32 v96, 48, v80
	v_or_b32_e32 v98, 56, v80
	v_lshl_add_u64 v[100:101], v[10:11], 0, s[42:43]
	v_lshl_add_u64 v[112:113], v[10:11], 0, s[34:35]
	s_cselect_b64 s[24:25], -1, 0
	v_mov_b32_e32 v87, v3
	v_mov_b32_e32 v89, v3
	v_mov_b32_e32 v91, v3
	v_mov_b32_e32 v93, v3
	v_mov_b32_e32 v95, v3
	v_mov_b32_e32 v97, v3
	v_mov_b32_e32 v99, v3
	v_lshl_add_u64 v[120:121], v[10:11], 0, s[8:9]
	s_addk_i32 s39, 0x3900
	s_branch .LBB0_1285
.Lc_q_tomix:
	v_mov_b32_e32 v5, -1
	ds_write_b32 v2, v5
	s_waitcnt vmcnt(0) lgkmcnt(0)
	s_barrier
	s_branch .Lc_mix_entry
.LBB0_1283:
	v_lshlrev_b32_e32 v2, 2, v0
	v_add_u32_e32 v2, 0x23580, v2
	ds_read_b32 v5, v2
	s_waitcnt lgkmcnt(0)
	v_readfirstlane_b32 s28, v5
	s_nop 3
	s_cmp_lt_i32 s28, 1
	s_cbranch_scc1 .Lc_q_cont
	v_add_u32_e32 v5, -1, v5
	s_cmp_eq_u32 s28, 1
	s_cbranch_scc1 .Lc_q_tomix
	ds_write_b32 v2, v5
	s_waitcnt lgkmcnt(0)

; __global__ void __launch_bounds__(NWAVES * 64, 2) fwd_kernel(Args args_unused) {
;     ...
;             for (;;) {
;                 __syncthreads();
;                 if (tid == 0) *qb = atomicAdd(qhead, 32u);
;                 __syncthreads();
;                 const int it0 = CV_A + (int)__builtin_amdgcn_readfirstlane(*qb);
;                 if (it0 >= CV_ALL) break;
.Lc_qexit:
	v_lshlrev_b32_e32 v2, 2, v0
	v_add_u32_e32 v2, 0x23580, v2
	ds_read_b32 v5, v2
	s_waitcnt lgkmcnt(0)
	v_readfirstlane_b32 s28, v5
	s_nop 3
	s_cmp_gt_i32 s28, 0
	s_cbranch_scc1 .Lc_q_tomix
	v_mov_b32_e32 v5, 0
	ds_write_b32 v2, v5
	s_waitcnt lgkmcnt(0)
